# v76 with the residual-norm row split 17/13 instead of 18/10 (sample waves take 13 prompt rows)
# baseline (speedup 1.0000x reference)
.LBB0_455:
	s_add_u32 s2, s8, 0xd100000
	s_addc_u32 s3, s9, 0
	s_abs_i32 s19, s18
	v_cvt_f32_u32_e32 v0, s19
	s_add_i32 s20, s18, 0x7fff
	s_sub_i32 s21, 0xffff8001, s18
	s_xor_b32 s18, s20, s18
	v_rcp_iflag_f32_e32 v0, v0
	s_max_i32 s20, s20, s21
	s_sub_i32 s21, 0, s19
	s_ashr_i32 s18, s18, 31
	v_mul_f32_e32 v0, 0x4f7ffffe, v0
	v_cvt_u32_f32_e32 v0, v0
	v_lshlrev_b32_e32 v122, 5, v24
	v_readfirstlane_b32 s22, v0
	s_mul_i32 s21, s21, s22
	s_mul_hi_u32 s21, s22, s21
	s_add_i32 s22, s22, s21
	s_mul_hi_u32 s21, s20, s22
	s_mul_i32 s22, s21, s19
	s_sub_i32 s20, s20, s22
	s_add_i32 s23, s21, 1
	s_sub_i32 s22, s20, s19
	s_cmp_ge_u32 s20, s19
	s_cselect_b32 s21, s23, s21
	s_cselect_b32 s20, s22, s20
	s_add_i32 s22, s21, 1
	s_cmp_ge_u32 s20, s19
	s_cselect_b32 s19, s22, s21
	s_xor_b32 s19, s19, s18
	s_sub_i32 s19, s19, s18
	s_mul_i32 s18, s19, s50
	s_add_i32 s19, s18, s19
	s_min_i32 s24, s19, 0x8000
	s_and_b32 s100, s50, 0xff
	s_lshr_b32 s101, s50, 8
	s_lshl_b32 s101, s101, 12
	s_mul_i32 s98, s100, 17
	s_add_i32 s98, s98, s101
	s_add_i32 s99, s100, 0xffffff40
	s_mul_i32 s99, s99, 13
	s_addk_i32 s99, 0xcc0
	s_add_i32 s99, s99, s101
	s_cmpk_lt_i32 s100, 0xc0
	s_cselect_b32 s18, s98, s99
	s_cselect_b32 s98, 17, 13
	s_add_i32 s24, s18, s98
	s_cmp_lt_i32 s18, s24
	s_cselect_b64 s[20:21], -1, 0
	s_cmp_ge_i32 s18, s24
	s_cbranch_scc1 .LBB0_458
	s_ashr_i32 s19, s18, 31
	s_lshl_b64 s[22:23], s[18:19], 12
	s_add_u32 s22, s6, s22
	s_addc_u32 s23, s7, s23
	global_load_dwordx4 v[100:103], v122, s[22:23] offset:16
	global_load_dwordx4 v[108:111], v122, s[22:23]
	global_load_dwordx4 v[96:99], v122, s[22:23] offset:2064
	global_load_dwordx4 v[104:107], v122, s[22:23] offset:2048
	s_lshl_b64 s[22:23], s[18:19], 11
	s_add_u32 s22, s2, s22
	s_addc_u32 s23, s3, s23
	global_load_dwordx4 v[116:119], v120, s[22:23]
	global_load_dwordx4 v[112:115], v120, s[22:23] offset:1024
	s_add_i32 s22, s18, 1
	s_cmp_ge_i32 s22, s24
	s_cbranch_scc0 .LBB0_459

.LBB0_674:
	s_add_u32 s2, s12, 0x54000000
	s_addc_u32 s3, s13, 0
	s_add_u32 s20, s14, 0xd100000
	s_addc_u32 s21, s15, 0
	s_abs_i32 s19, s18
	v_cvt_f32_u32_e32 v0, s19
	s_add_i32 s22, s18, 0x7fff
	s_sub_i32 s23, 0xffff8001, s18
	s_xor_b32 s18, s22, s18
	v_rcp_iflag_f32_e32 v0, v0
	s_max_i32 s22, s22, s23
	s_sub_i32 s23, 0, s19
	s_ashr_i32 s18, s18, 31
	v_mul_f32_e32 v0, 0x4f7ffffe, v0
	v_cvt_u32_f32_e32 v0, v0
	s_nop 0
	v_readfirstlane_b32 s24, v0
	s_mul_i32 s23, s23, s24
	s_mul_hi_u32 s23, s24, s23
	s_add_i32 s24, s24, s23
	s_mul_hi_u32 s23, s22, s24
	s_mul_i32 s24, s23, s19
	s_sub_i32 s22, s22, s24
	s_add_i32 s25, s23, 1
	s_sub_i32 s24, s22, s19
	s_cmp_ge_u32 s22, s19
	s_cselect_b32 s23, s25, s23
	s_cselect_b32 s22, s24, s22
	s_add_i32 s24, s23, 1
	s_cmp_ge_u32 s22, s19
	s_cselect_b32 s19, s24, s23
	s_xor_b32 s19, s19, s18
	s_sub_i32 s19, s19, s18
	s_mul_i32 s18, s19, s48
	s_add_i32 s19, s18, s19
	s_min_i32 s26, s19, 0x8000
	s_and_b32 s100, s48, 0xff
	s_lshr_b32 s101, s48, 8
	s_lshl_b32 s101, s101, 12
	s_mul_i32 s98, s100, 17
	s_add_i32 s98, s98, s101
	s_add_i32 s99, s100, 0xffffff40
	s_mul_i32 s99, s99, 13
	s_addk_i32 s99, 0xcc0
	s_add_i32 s99, s99, s101
	s_cmpk_lt_i32 s100, 0xc0
	s_cselect_b32 s18, s98, s99
	s_cselect_b32 s98, 17, 13
	s_add_i32 s26, s18, s98
	s_cmp_lt_i32 s18, s26
	s_cselect_b64 s[22:23], -1, 0
	s_cmp_ge_i32 s18, s26
	s_cbranch_scc1 .LBB0_676
	s_ashr_i32 s19, s18, 31
	s_lshl_b64 s[24:25], s[18:19], 11
	s_add_u32 s34, s20, s24
	s_addc_u32 s35, s21, s25
	s_add_u32 s24, s2, s24
	s_addc_u32 s25, s3, s25
	global_load_dwordx4 v[84:87], v96, s[24:25]
	global_load_dwordx4 v[80:83], v96, s[24:25] offset:1024
	global_load_dwordx4 v[92:95], v96, s[34:35]
	global_load_dwordx4 v[88:91], v96, s[34:35] offset:1024

.LBB0_1179:
	s_add_u32 s2, s12, 0x54000000
	s_addc_u32 s3, s13, 0
	s_add_u32 s20, s14, 0xd100000
	s_addc_u32 s21, s15, 0
	s_abs_i32 s19, s18
	v_cvt_f32_u32_e32 v0, s19
	s_add_i32 s22, s18, 0x7fff
	s_sub_i32 s23, 0xffff8001, s18
	s_xor_b32 s18, s22, s18
	v_rcp_iflag_f32_e32 v0, v0
	s_max_i32 s22, s22, s23
	s_sub_i32 s23, 0, s19
	s_ashr_i32 s18, s18, 31
	v_mul_f32_e32 v0, 0x4f7ffffe, v0
	v_cvt_u32_f32_e32 v0, v0
	s_nop 0
	v_readfirstlane_b32 s24, v0
	s_mul_i32 s23, s23, s24
	s_mul_hi_u32 s23, s24, s23
	s_add_i32 s24, s24, s23
	s_mul_hi_u32 s23, s22, s24
	s_mul_i32 s24, s23, s19
	s_sub_i32 s22, s22, s24
	s_add_i32 s25, s23, 1
	s_sub_i32 s24, s22, s19
	s_cmp_ge_u32 s22, s19
	s_cselect_b32 s23, s25, s23
	s_cselect_b32 s22, s24, s22
	s_add_i32 s24, s23, 1
	s_cmp_ge_u32 s22, s19
	s_cselect_b32 s19, s24, s23
	s_xor_b32 s19, s19, s18
	s_sub_i32 s19, s19, s18
	s_mul_i32 s18, s19, s34
	s_add_i32 s19, s18, s19
	s_min_i32 s26, s19, 0x8000
	s_and_b32 s100, s34, 0xff
	s_lshr_b32 s101, s34, 8
	s_lshl_b32 s101, s101, 12
	s_mul_i32 s98, s100, 17
	s_add_i32 s98, s98, s101
	s_add_i32 s99, s100, 0xffffff40
	s_mul_i32 s99, s99, 13
	s_addk_i32 s99, 0xcc0
	s_add_i32 s99, s99, s101
	s_cmpk_lt_i32 s100, 0xc0
	s_cselect_b32 s18, s98, s99
	s_cselect_b32 s98, 17, 13
	s_add_i32 s26, s18, s98
	s_cmp_lt_i32 s18, s26
	s_cselect_b64 s[22:23], -1, 0
	s_cmp_ge_i32 s18, s26
	s_cbranch_scc1 .LBB0_1181
	s_ashr_i32 s19, s18, 31
	s_lshl_b64 s[24:25], s[18:19], 11
	s_add_u32 s34, s20, s24
	s_addc_u32 s35, s21, s25
	s_add_u32 s24, s2, s24
	s_addc_u32 s25, s3, s25
	global_load_dwordx4 v[84:87], v96, s[24:25]
	global_load_dwordx4 v[80:83], v96, s[24:25] offset:1024
	global_load_dwordx4 v[92:95], v96, s[34:35]
	global_load_dwordx4 v[88:91], v96, s[34:35] offset:1024

.LBB0_2880:
	s_add_u32 s0, s4, 0x54000000
	s_addc_u32 s1, s5, 0
	s_add_u32 s14, s6, 0xd100000
	s_addc_u32 s15, s7, 0
	s_abs_i32 s13, s12
	v_cvt_f32_u32_e32 v0, s13
	s_add_i32 s16, s12, 0x7fff
	s_sub_i32 s17, 0xffff8001, s12
	s_xor_b32 s12, s16, s12
	v_rcp_iflag_f32_e32 v0, v0
	s_max_i32 s16, s16, s17
	s_sub_i32 s17, 0, s13
	s_ashr_i32 s12, s12, 31
	v_mul_f32_e32 v0, 0x4f7ffffe, v0
	v_cvt_u32_f32_e32 v0, v0
	s_nop 0
	v_readfirstlane_b32 s18, v0
	s_mul_i32 s17, s17, s18
	s_mul_hi_u32 s17, s18, s17
	s_add_i32 s18, s18, s17
	s_mul_hi_u32 s17, s16, s18
	s_mul_i32 s18, s17, s13
	s_sub_i32 s16, s16, s18
	s_add_i32 s19, s17, 1
	s_sub_i32 s18, s16, s13
	s_cmp_ge_u32 s16, s13
	s_cselect_b32 s17, s19, s17
	s_cselect_b32 s16, s18, s16
	s_add_i32 s18, s17, 1
	s_cmp_ge_u32 s16, s13
	s_cselect_b32 s13, s18, s17
	s_xor_b32 s13, s13, s12
	s_sub_i32 s13, s13, s12
	s_mul_i32 s12, s13, s33
	s_add_i32 s13, s12, s13
	s_min_i32 s20, s13, 0x8000
	s_and_b32 s100, s33, 0xff
	s_lshr_b32 s101, s33, 8
	s_lshl_b32 s101, s101, 12
	s_mul_i32 s98, s100, 17
	s_add_i32 s98, s98, s101
	s_add_i32 s99, s100, 0xffffff40
	s_mul_i32 s99, s99, 13
	s_addk_i32 s99, 0xcc0
	s_add_i32 s99, s99, s101
	s_cmpk_lt_i32 s100, 0xc0
	s_cselect_b32 s12, s98, s99
	s_cselect_b32 s98, 17, 13
	s_add_i32 s20, s12, s98
	s_cmp_lt_i32 s12, s20
	s_cselect_b64 s[16:17], -1, 0
	s_cmp_ge_i32 s12, s20
	s_cbranch_scc1 .LBB0_2882
	s_ashr_i32 s13, s12, 31
	s_lshl_b64 s[18:19], s[12:13], 11
	s_add_u32 s22, s14, s18
	s_addc_u32 s23, s15, s19
	s_add_u32 s18, s0, s18
	s_addc_u32 s19, s1, s19
	global_load_dwordx4 v[52:55], v64, s[18:19]
	global_load_dwordx4 v[48:51], v64, s[18:19] offset:1024
	global_load_dwordx4 v[60:63], v64, s[22:23]
	global_load_dwordx4 v[56:59], v64, s[22:23] offset:1024
